# prologue de-serialisation: PRE constant-table fill batched (scalar-selected pointers, loads in flight together) instead of a serial per-element loop
# speedup vs baseline: 1.0187x; 1.0002x over previous
.LBB0_28:
	s_and_b64 vcc, exec, s[0:1]
	s_cbranch_vccz .LBB0_643
	s_mov_b64 s[0:1], s[94:95]
	s_load_dwordx2 s[30:31], s[0:1], 0xb0
	v_mbcnt_lo_u32_b32 v180, -1, 0
	v_mbcnt_hi_u32_b32 v180, -1, v180
	v_readlane_b32 s66, v252, 3
	s_lshl_b32 s42, s66, 6
	s_waitcnt vmcnt(0) lgkmcnt(0)
	v_mov_b32_e32 v3, v180
	s_movk_i32 s0, 0x440
	v_add_u32_e32 v2, s42, v3
	s_mov_b64 s[36:37], s[94:95]
	s_mov_b64 s[26:27], s[94:95]
	v_cmp_gt_i32_e32 vcc, s0, v2
	s_and_saveexec_b64 s[24:25], vcc
	s_cbranch_execz .LBB0_62
	v_readlane_b32 s26, v254, 63
	v_readlane_b32 s27, v252, 16
	s_nop 0
	s_lshl_b32 s0, s66, 3
	s_add_u32 s0, s0, 0x60
	s_lshl_b32 s1, s26, 9
	s_add_u32 s1, s1, s27
	s_cmp_lt_u32 s66, 3
	s_cbranch_scc1 .Lcta_done
	s_sub_u32 s3, s66, 3
	s_cmp_lt_u32 s3, 4
	s_cbranch_scc0 .Lcta_7
	s_lshr_b32 s0, s3, 1
	s_lshl_b32 s0, s0, 4
	s_add_u32 s0, s0, 0x38
	s_and_b32 s3, s3, 1
	s_lshl_b32 s1, s26, 1
	s_add_u32 s1, s1, s3
	s_lshl_b32 s1, s1, 9
	s_add_u32 s1, s1, s27
	s_branch .Lcta_done
.Lcta_7:
	s_sub_u32 s3, s66, 7
	s_cmp_lt_u32 s3, 6
	s_cbranch_scc0 .Lcta_13
	s_and_b32 s0, s3, 1
	s_lshl_b32 s0, s0, 3
	s_add_u32 s0, s0, 0x28
	s_lshr_b32 s3, s3, 1
	s_lshl_b32 s3, s3, 9
	s_mul_i32 s1, s26, 0x700
	s_add_u32 s1, s1, s3
	s_add_u32 s1, s1, s27
	s_branch .Lcta_done
.Lcta_13:
	s_sub_u32 s3, s66, 13
	s_lshr_b32 s0, s3, 1
	s_lshl_b32 s0, s0, 3
	s_add_u32 s0, s0, 0x28
	s_and_b32 s3, s3, 1
	s_lshl_b32 s3, s3, 6
	s_mul_i32 s1, s26, 0x700
	s_add_u32 s1, s1, s3
	s_add_u32 s1, s1, 0x600
.Lcta_done:
	s_load_dwordx2 s[36:37], s[94:95], s0
	s_add_u32 s50, s66, 8
	s_lshl_b32 s28, s50, 3
	s_add_u32 s28, s28, 0x60
	s_lshl_b32 s29, s26, 9
	s_add_u32 s29, s29, s27
	s_cmp_lt_u32 s50, 3
	s_cbranch_scc1 .Lctb_done
	s_sub_u32 s3, s50, 3
	s_cmp_lt_u32 s3, 4
	s_cbranch_scc0 .Lctb_7
	s_lshr_b32 s28, s3, 1
	s_lshl_b32 s28, s28, 4
	s_add_u32 s28, s28, 0x38
	s_and_b32 s3, s3, 1
	s_lshl_b32 s29, s26, 1
	s_add_u32 s29, s29, s3
	s_lshl_b32 s29, s29, 9
	s_add_u32 s29, s29, s27
	s_branch .Lctb_done
.Lctb_7:
	s_sub_u32 s3, s50, 7
	s_cmp_lt_u32 s3, 6
	s_cbranch_scc0 .Lctb_13
	s_and_b32 s28, s3, 1
	s_lshl_b32 s28, s28, 3
	s_add_u32 s28, s28, 0x28
	s_lshr_b32 s3, s3, 1
	s_lshl_b32 s3, s3, 9
	s_mul_i32 s29, s26, 0x700
	s_add_u32 s29, s29, s3
	s_add_u32 s29, s29, s27
	s_branch .Lctb_done
.Lctb_13:
	s_sub_u32 s3, s50, 13
	s_lshr_b32 s28, s3, 1
	s_lshl_b32 s28, s28, 3
	s_add_u32 s28, s28, 0x28
	s_and_b32 s3, s3, 1
	s_lshl_b32 s3, s3, 6
	s_mul_i32 s29, s26, 0x700
	s_add_u32 s29, s29, s3
	s_add_u32 s29, s29, 0x600
.Lctb_done:
	s_load_dwordx2 s[38:39], s[94:95], s28
	v_add_lshl_u32 v1, s1, v180, 2
	v_add_lshl_u32 v4, s29, v180, 2
	s_lshl_b32 s3, s66, 8
	s_add_u32 s3, s3, 0x24700
	v_lshl_add_u32 v8, v180, 2, s3
	s_cmp_lg_u32 s66, 0
	s_cbranch_scc1 .Lct_two
	s_mov_b32 s50, 16
	s_lshl_b32 s40, s50, 3
	s_add_u32 s40, s40, 0x60
	s_lshl_b32 s41, s26, 9
	s_add_u32 s41, s41, s27
	s_cmp_lt_u32 s50, 3
	s_cbranch_scc1 .Lctc_done
	s_sub_u32 s3, s50, 3
	s_cmp_lt_u32 s3, 4
	s_cbranch_scc0 .Lctc_7
	s_lshr_b32 s40, s3, 1
	s_lshl_b32 s40, s40, 4
	s_add_u32 s40, s40, 0x38
	s_and_b32 s3, s3, 1
	s_lshl_b32 s41, s26, 1
	s_add_u32 s41, s41, s3
	s_lshl_b32 s41, s41, 9
	s_add_u32 s41, s41, s27
	s_branch .Lctc_done
.Lctc_7:
	s_sub_u32 s3, s50, 7
	s_cmp_lt_u32 s3, 6
	s_cbranch_scc0 .Lctc_13
	s_and_b32 s40, s3, 1
	s_lshl_b32 s40, s40, 3
	s_add_u32 s40, s40, 0x28
	s_lshr_b32 s3, s3, 1
	s_lshl_b32 s3, s3, 9
	s_mul_i32 s41, s26, 0x700
	s_add_u32 s41, s41, s3
	s_add_u32 s41, s41, s27
	s_branch .Lctc_done
.Lctc_13:
	s_sub_u32 s3, s50, 13
	s_lshr_b32 s40, s3, 1
	s_lshl_b32 s40, s40, 3
	s_add_u32 s40, s40, 0x28
	s_and_b32 s3, s3, 1
	s_lshl_b32 s3, s3, 6
	s_mul_i32 s41, s26, 0x700
	s_add_u32 s41, s41, s3
	s_add_u32 s41, s41, 0x600
.Lctc_done:
	s_load_dwordx2 s[48:49], s[94:95], s40
	v_add_lshl_u32 v9, s41, v180, 2
	s_waitcnt lgkmcnt(0)
	global_load_dword v5, v1, s[36:37]
	global_load_dword v6, v4, s[38:39]
	global_load_dword v7, v9, s[48:49]
	s_waitcnt vmcnt(0)
	ds_write_b32 v8, v5
	ds_write_b32 v8, v6 offset:2048
	ds_write_b32 v8, v7 offset:4096
	s_branch .Lct_end
.Lct_two:
	s_waitcnt lgkmcnt(0)
	global_load_dword v5, v1, s[36:37]
	global_load_dword v6, v4, s[38:39]
	s_waitcnt vmcnt(0)
	ds_write_b32 v8, v5
	ds_write_b32 v8, v6 offset:2048
.Lct_end:
.LBB0_62:
	s_or_b64 exec, exec, s[24:25]
	v_mov_b32_e32 v3, v180
	s_waitcnt lgkmcnt(0)
	s_barrier
	v_readlane_b32 s0, v252, 18
	v_add_u32_e32 v1, s42, v3
	v_ashrrev_i32_e32 v1, 3, v1
	v_add_u32_e32 v1, s0, v1
	v_readlane_b32 s0, v252, 19
	v_lshlrev_b32_e32 v3, 3, v3
	s_waitcnt lgkmcnt(0)
	s_mov_b64 s[98:99], s[30:31]
	s_add_u32 s24, s30, 0x7c00000
	v_add_u32_e32 v2, s0, v1
	v_and_b32_e32 v8, 56, v3
	v_ashrrev_i32_e32 v3, 31, v2
	s_addc_u32 s25, s31, 0
	v_lshlrev_b64 v[4:5], 9, v[2:3]
	v_writelane_b32 v255, s24, 3
	v_lshlrev_b32_e32 v6, 1, v8
	v_mov_b32_e32 v7, v0
	v_lshl_add_u64 v[2:3], s[24:25], 0, v[4:5]
	v_lshl_add_u64 v[6:7], v[2:3], 0, v[6:7]
	global_load_dwordx4 v[100:103], v[6:7], off
	v_mov_b32_e32 v106, v0
	v_mov_b32_e32 v107, v0
	v_mov_b32_e32 v104, v0
	v_mov_b32_e32 v105, v0
	v_mov_b64_e32 v[110:111], v[106:107]
	v_writelane_b32 v255, s25, 4
	v_cmp_lt_i32_e32 vcc, 0, v1
	v_mov_b64_e32 v[108:109], v[104:105]
	s_and_saveexec_b64 s[26:27], vcc
	s_cbranch_execz .LBB0_64
	global_load_dwordx4 v[108:111], v[6:7], off offset:-512
